# NA bias/mask LDS reads double-buffered in batches of 6 (on top of v21)
# speedup vs baseline: 1.0068x; 1.0068x over previous
; __device__ __forceinline__ void na_item(const Params& p, int item, char* lds) {
;     ...
;   const int band = (n == 0) ? 0 : (n == 1) ? 8 : (n == 2) ? 24 : 32;
;   f32x4 s[16];
; #pragma unroll
;   for (int ch = 0; ch < 8; ++ch)
; #pragma unroll
;     for (int ab = 0; ab < 2; ++ab) {
;       const int slot = 8 * (lr >> 2) + 4 * ab + (lr & 3);
;       const int krow = (half == 0) ? (ch * 64 + band + slot) : (512 + ch * 32 + slot);
;       f32x4 a = (f32x4){0.f, 0.f, 0.f, 0.f};
; #pragma unroll
;       for (int ks = 0; ks < 2; ++ks) {
;         const bf16x8 kf = *(const bf16x8*)(lds + krow * 144 + ks * 64 + lq * 16);
;         a = __builtin_amdgcn_mfma_f32_16x16x32_bf16(kf, qf[ks], a, 0, 0, 0);
;       }
;       s[ch * 2 + ab] = a;
;     }
.LBB0_517:
	s_or_b64 exec, exec, s[6:7]
	v_lshlrev_b32_e32 v9, 1, v173
	v_and_b32_e32 v10, 3, v147
	v_cmp_gt_u32_e32 vcc, s62, v147
	v_and_or_b32 v9, v9, 24, v10
	v_add_u32_e32 v18, 0, v158
	v_cndmask_b32_e32 v14, v157, v73, vcc
	v_add_u32_e32 v10, v14, v9
	v_mad_u32_u24 v15, v10, s60, v18
	ds_read_b128 v[10:13], v15
	v_or_b32_e32 v19, 4, v9
	v_add_u32_e32 v22, v14, v19
	ds_read_b128 v[14:17], v15 offset:64
	v_mad_u32_u24 v26, v22, s60, v18
	s_waitcnt vmcnt(1) lgkmcnt(1)
	v_mfma_f32_16x16x32_bf16 v[10:13], v[10:13], v[4:7], 0
	ds_read_b128 v[22:25], v26
	ds_read_b128 v[30:33], v26 offset:64
	s_lshl_b32 s6, s38, 9
	s_or_b32 s6, s6, s40
	s_waitcnt vmcnt(0) lgkmcnt(2)
	v_mfma_f32_16x16x32_bf16 v[140:143], v[14:17], v[0:3], v[10:13]
	v_lshlrev_b32_e32 v144, 7, v8
	v_ashrrev_i32_e32 v174, 6, v37
	v_ashrrev_i32_e32 v175, 6, v44
	v_or_b32_e32 v10, 64, v73
	v_cndmask_b32_e32 v26, v162, v10, vcc
	v_add_u32_e32 v10, v26, v9
	v_mad_u32_u24 v14, v10, s60, v18
	ds_read_b128 v[10:13], v14
	ds_read_b128 v[14:17], v14 offset:64
	s_waitcnt lgkmcnt(1)
	v_mfma_f32_16x16x32_bf16 v[10:13], v[10:13], v[4:7], 0
	v_ashrrev_i32_e32 v176, 6, v45
	v_ashrrev_i32_e32 v177, 6, v20
	v_ashrrev_i32_e32 v178, 6, v21
	v_mfma_f32_16x16x32_bf16 v[22:25], v[22:25], v[4:7], 0
	v_ashrrev_i32_e32 v179, 6, v28
	v_ashrrev_i32_e32 v180, 6, v29
	v_add_u32_e32 v20, s6, v178
	s_waitcnt lgkmcnt(0)
	v_mfma_f32_16x16x32_bf16 v[132:135], v[14:17], v[0:3], v[10:13]
	v_add_u32_e32 v28, s6, v180
	v_ashrrev_i32_e32 v21, 31, v20
	v_ashrrev_i32_e32 v29, 31, v28
	v_add_u32_e32 v10, v26, v19
	v_mad_u32_u24 v14, v10, s60, v18
	v_mfma_f32_16x16x32_bf16 v[136:139], v[30:33], v[0:3], v[22:25]
	ds_read_b128 v[10:13], v14
	ds_read_b128 v[14:17], v14 offset:64
	v_lshlrev_b64 v[20:21], 12, v[20:21]
	v_or_b32_e32 v22, 0x80, v73
	v_cndmask_b32_e32 v26, v163, v22, vcc
	v_add_u32_e32 v22, v26, v9
	v_mad_u32_u24 v27, v22, s60, v18
	s_waitcnt lgkmcnt(1)
	v_mfma_f32_16x16x32_bf16 v[10:13], v[10:13], v[4:7], 0
	ds_read_b128 v[22:25], v27
	v_lshlrev_b64 v[28:29], 12, v[28:29]
	v_lshl_add_u64 v[20:21], s[10:11], 0, v[20:21]
	s_waitcnt lgkmcnt(1)
	v_mfma_f32_16x16x32_bf16 v[124:127], v[14:17], v[0:3], v[10:13]
	v_lshl_add_u64 v[28:29], s[10:11], 0, v[28:29]
	v_lshlrev_b32_e32 v160, 4, v159
	v_mov_b32_e32 v161, v145
	ds_read_b128 v[10:13], v27 offset:64
	s_waitcnt lgkmcnt(1)
	v_mfma_f32_16x16x32_bf16 v[14:17], v[22:25], v[4:7], 0
	v_or_b32_e32 v22, 0xc0, v73
	v_lshl_add_u64 v[20:21], v[20:21], 0, v[144:145]
	v_lshl_add_u64 v[28:29], v[28:29], 0, v[144:145]
	s_waitcnt lgkmcnt(0)
	v_mfma_f32_16x16x32_bf16 v[116:119], v[10:13], v[0:3], v[14:17]
	v_add_u32_e32 v10, v26, v19
	s_nop 1
	v_mad_u32_u24 v14, v10, s60, v18
	ds_read_b128 v[10:13], v14
	ds_read_b128 v[14:17], v14 offset:64
	v_cndmask_b32_e32 v26, v164, v22, vcc
	v_add_u32_e32 v22, v26, v9
	v_mad_u32_u24 v27, v22, s60, v18
	s_waitcnt lgkmcnt(1)
	v_mfma_f32_16x16x32_bf16 v[10:13], v[10:13], v[4:7], 0
	ds_read_b128 v[22:25], v27
	v_lshl_add_u64 v[20:21], v[20:21], 0, v[160:161]
	v_lshl_add_u64 v[28:29], v[28:29], 0, v[160:161]
	s_waitcnt lgkmcnt(1)
	v_mfma_f32_16x16x32_bf16 v[108:111], v[14:17], v[0:3], v[10:13]
	v_ashrrev_i32_e32 v181, 5, v37
	v_ashrrev_i32_e32 v182, 5, v44
	v_ashrrev_i32_e32 v183, 5, v45
	ds_read_b128 v[10:13], v27 offset:64
	s_waitcnt lgkmcnt(1)
	v_mfma_f32_16x16x32_bf16 v[14:17], v[22:25], v[4:7], 0
	v_or_b32_e32 v22, 0x100, v73
	v_add_u32_e32 v46, s6, v182
	v_add_u32_e32 v44, s6, v183
	s_waitcnt lgkmcnt(0)
	v_mfma_f32_16x16x32_bf16 v[100:103], v[10:13], v[0:3], v[14:17]
	v_add_u32_e32 v10, v26, v19
	s_nop 1
	v_mad_u32_u24 v14, v10, s60, v18
	v_cndmask_b32_e32 v26, v165, v22, vcc
	ds_read_b128 v[10:13], v14
	ds_read_b128 v[14:17], v14 offset:64
	v_add_u32_e32 v22, v26, v9
	v_mad_u32_u24 v27, v22, s60, v18
	ds_read_b128 v[22:25], v27
	s_waitcnt lgkmcnt(2)
	v_mfma_f32_16x16x32_bf16 v[10:13], v[10:13], v[4:7], 0
	v_ashrrev_i32_e32 v47, 31, v46
	v_ashrrev_i32_e32 v45, 31, v44
	v_lshlrev_b64 v[46:47], 9, v[46:47]
	s_waitcnt lgkmcnt(1)
	v_mfma_f32_16x16x32_bf16 v[88:91], v[14:17], v[0:3], v[10:13]
	v_lshlrev_b64 v[44:45], 9, v[44:45]
	v_lshl_add_u64 v[46:47], s[18:19], 0, v[46:47]
	v_lshl_add_u64 v[44:45], s[18:19], 0, v[44:45]
	ds_read_b128 v[10:13], v27 offset:64
	s_waitcnt lgkmcnt(1)
	v_mfma_f32_16x16x32_bf16 v[14:17], v[22:25], v[4:7], 0
	v_add_u32_e32 v22, v26, v19
	v_mad_u32_u24 v26, v22, s60, v18
	ds_read_b128 v[22:25], v26
	s_waitcnt lgkmcnt(1)
	v_mfma_f32_16x16x32_bf16 v[80:83], v[10:13], v[0:3], v[14:17]
	ds_read_b128 v[10:13], v26 offset:64
	v_or_b32_e32 v26, 0x140, v73
	v_add_u32_e32 v184, v73, v146
	s_waitcnt lgkmcnt(1)
	v_mfma_f32_16x16x32_bf16 v[14:17], v[22:25], v[4:7], 0
	v_cndmask_b32_e32 v22, v166, v26, vcc
	v_add_u32_e32 v23, v22, v9
	v_mad_u32_u24 v23, v23, s60, v18
	s_waitcnt lgkmcnt(0)
	v_mfma_f32_16x16x32_bf16 v[76:79], v[10:13], v[0:3], v[14:17]
	ds_read_b128 v[10:13], v23
	s_nop 1
	ds_read_b128 v[14:17], v23 offset:64
	v_add_u32_e32 v22, v22, v19
	v_mad_u32_u24 v26, v22, s60, v18
	s_waitcnt lgkmcnt(1)
	v_mfma_f32_16x16x32_bf16 v[10:13], v[10:13], v[4:7], 0
	ds_read_b128 v[22:25], v26
	ds_read_b128 v[30:33], v26 offset:64
	s_waitcnt lgkmcnt(2)
	v_mfma_f32_16x16x32_bf16 v[68:71], v[14:17], v[0:3], v[10:13]
	s_nop 3
	v_or_b32_e32 v10, 0x180, v73
	v_cndmask_b32_e32 v26, v167, v10, vcc
	v_add_u32_e32 v14, v26, v9
	s_waitcnt lgkmcnt(1)
	v_mfma_f32_16x16x32_bf16 v[10:13], v[22:25], v[4:7], 0
	v_mad_u32_u24 v22, v14, s60, v18
	ds_read_b128 v[14:17], v22
	ds_read_b128 v[22:25], v22 offset:64
	s_waitcnt lgkmcnt(2)
	v_mfma_f32_16x16x32_bf16 v[64:67], v[30:33], v[0:3], v[10:13]
	s_nop 2
	v_add_u32_e32 v10, v26, v19
	v_mad_u32_u24 v26, v10, s60, v18
	ds_read_b128 v[10:13], v26
	ds_read_b128 v[30:33], v26 offset:64
	s_waitcnt lgkmcnt(3)
; __device__ __forceinline__ void na_item(const Params& p, int item, char* lds) {
;     ...
;   NA_VL(0) NA_VL(1) NA_VL(2) NA_VL(3) NA_VL(4) NA_VL(5) NA_VL(6) NA_VL(7)
;   NA_VC(0) NA_VC(1) NA_VC(2) NA_VC(3)
;   if (half == 0) {
;     const int qc = n * 16 + lr;
;     const int wstart = min(max(qc - 8, 0), 48);
; #pragma unroll
;     for (int ch = 0; ch < 8; ++ch)
; #pragma unroll
;       for (int ab = 0; ab < 2; ++ab)
; #pragma unroll
;         for (int e = 0; e < 4; ++e) {
;           const int kcol = band + 8 * lq + 4 * ab + e;
;           const bool inw = (kcol >= wstart) && (kcol < wstart + 16);
;           const int ci = min(max(kcol - qc + 15, 0), 30);
	v_mfma_f32_16x16x32_bf16 v[14:17], v[14:17], v[4:7], 0
	v_or_b32_e32 v26, 0x1c0, v73
	v_cndmask_b32_e32 v26, v168, v26, vcc
	v_add_u32_e32 v9, v26, v9
	v_mad_u32_u24 v9, v9, s60, v18
	s_waitcnt lgkmcnt(2)
	v_mfma_f32_16x16x32_bf16 v[60:63], v[22:25], v[0:3], v[14:17]
	ds_read_b128 v[22:25], v9 offset:64
	s_nop 1
	ds_read_b128 v[14:17], v9
	s_waitcnt lgkmcnt(3)
	v_mfma_f32_16x16x32_bf16 v[10:13], v[10:13], v[4:7], 0
	v_add_u32_e32 v9, v26, v19
	v_mad_u32_u24 v9, v9, s60, v18
	v_add_u32_e32 v18, s6, v171
	s_waitcnt lgkmcnt(0)
	v_mfma_f32_16x16x32_bf16 v[14:17], v[14:17], v[4:7], 0
	v_ashrrev_i32_e32 v19, 31, v18
	v_mfma_f32_16x16x32_bf16 v[56:59], v[30:33], v[0:3], v[10:13]
	s_nop 2
	ds_read_b128 v[10:13], v9
	ds_read_b128 v[84:87], v9 offset:64
	v_add_u32_e32 v30, s6, v179
	v_ashrrev_i32_e32 v31, 31, v30
	v_mfma_f32_16x16x32_bf16 v[52:55], v[22:25], v[0:3], v[14:17]
	v_add_u32_e32 v22, s6, v177
	v_ashrrev_i32_e32 v23, 31, v22
	v_lshlrev_b64 v[22:23], 12, v[22:23]
	v_lshlrev_b64 v[14:15], 12, v[18:19]
	v_lshl_add_u64 v[14:15], s[10:11], 0, v[14:15]
	s_waitcnt lgkmcnt(1)
	v_mfma_f32_16x16x32_bf16 v[92:95], v[10:13], v[4:7], 0
	v_lshl_add_u64 v[4:5], v[14:15], 0, v[144:145]
	v_add_u32_e32 v6, s6, v174
	v_add_u32_e32 v12, s6, v175
	v_add_u32_e32 v14, s6, v176
	v_ashrrev_i32_e32 v7, 31, v6
	v_ashrrev_i32_e32 v13, 31, v12
	v_ashrrev_i32_e32 v15, 31, v14
	v_lshlrev_b64 v[6:7], 12, v[6:7]
	v_lshlrev_b64 v[12:13], 12, v[12:13]
	v_lshlrev_b64 v[14:15], 12, v[14:15]
	v_lshlrev_b64 v[30:31], 12, v[30:31]
	v_lshl_add_u64 v[6:7], s[10:11], 0, v[6:7]
	v_lshl_add_u64 v[12:13], s[10:11], 0, v[12:13]
	v_lshl_add_u64 v[14:15], s[10:11], 0, v[14:15]
	v_lshl_add_u64 v[22:23], s[10:11], 0, v[22:23]
	v_lshl_add_u64 v[30:31], s[10:11], 0, v[30:31]
	v_lshl_add_u64 v[6:7], v[6:7], 0, v[144:145]
	v_lshl_add_u64 v[12:13], v[12:13], 0, v[144:145]
	v_lshl_add_u64 v[14:15], v[14:15], 0, v[144:145]
	v_lshl_add_u64 v[22:23], v[22:23], 0, v[144:145]
	v_lshl_add_u64 v[30:31], v[30:31], 0, v[144:145]
	v_lshl_add_u64 v[4:5], v[4:5], 0, v[160:161]
	v_lshl_add_u64 v[6:7], v[6:7], 0, v[160:161]
	v_lshl_add_u64 v[12:13], v[12:13], 0, v[160:161]
	v_lshl_add_u64 v[14:15], v[14:15], 0, v[160:161]
	v_lshl_add_u64 v[22:23], v[22:23], 0, v[160:161]
	v_lshl_add_u64 v[30:31], v[30:31], 0, v[160:161]
	v_ashrrev_i32_e32 v161, 5, v147
	v_add_u32_e32 v38, s6, v161
	v_lshlrev_b32_e32 v144, 4, v36
	v_add_u32_e32 v36, s6, v181
	v_ashrrev_i32_e32 v39, 31, v38
	v_ashrrev_i32_e32 v37, 31, v36
	v_lshlrev_b64 v[38:39], 9, v[38:39]
	v_lshlrev_b64 v[36:37], 9, v[36:37]
	v_lshl_add_u64 v[38:39], s[18:19], 0, v[38:39]
	v_lshl_add_u64 v[36:37], s[18:19], 0, v[36:37]
	v_lshl_add_u64 v[38:39], v[38:39], 0, v[144:145]
	v_lshl_add_u64 v[36:37], v[36:37], 0, v[144:145]
	v_lshl_add_u64 v[46:47], v[46:47], 0, v[144:145]
	v_lshl_add_u64 v[44:45], v[44:45], 0, v[144:145]
	global_load_dwordx4 v[8:11], v[4:5], off
	s_nop 0
	global_load_dwordx4 v[4:7], v[6:7], off
	s_nop 0
	global_load_dwordx4 v[16:19], v[12:13], off
	s_nop 0
	global_load_dwordx4 v[12:15], v[14:15], off
	s_nop 0
	global_load_dwordx4 v[24:27], v[22:23], off
	s_nop 0
	global_load_dwordx4 v[20:23], v[20:21], off
	s_nop 0
	global_load_dwordx4 v[32:35], v[30:31], off
	s_nop 0
	global_load_dwordx4 v[28:31], v[28:29], off
	s_nop 0
	global_load_dwordx4 v[40:43], v[38:39], off
	s_nop 0
	global_load_dwordx4 v[36:39], v[36:37], off
	s_nop 0
	global_load_dwordx4 v[48:51], v[46:47], off
	s_nop 0
	global_load_dwordx4 v[44:47], v[44:45], off
	s_waitcnt lgkmcnt(0)
	v_mfma_f32_16x16x32_bf16 v[0:3], v[84:87], v[0:3], v[92:95]
	v_cmp_lt_u32_e64 s[6:7], s63, v147
	s_and_saveexec_b64 s[8:9], s[6:7]
	s_xor_b64 s[6:7], exec, s[8:9]
	v_add_u32_e32 v184, v73, v146
	s_or_saveexec_b64 s[38:39], s[6:7]
	v_mov_b32_e32 v185, 0x210
	s_xor_b64 exec, exec, s[38:39]
	s_cbranch_execz .LBB0_649
	v_or_b32_e32 v92, v72, v173
	v_sub_u32_e64 v72, v92, 8 clamp
	v_min_u32_e32 v93, 48, v72
	v_add_u32_e32 v94, 16, v93
	v_add_u32_e32 v243, 0, v184
	v_cmp_ge_u32_e64 s[6:7], v243, v93
	v_cmp_lt_u32_e64 s[8:9], v243, v94
	v_sub_u32_e32 v244, v243, v92
	s_and_b64 s[98:99], s[6:7], s[8:9]
	v_max_i32_e32 v244, -15, v244
	v_add_u32_e32 v244, 15, v244
	v_min_u32_e32 v244, 30, v244
	v_cndmask_b32_e64 v244, 31, v244, s[98:99]
	v_lshl_add_u32 v244, v244, 2, 0
	v_add_u32_e32 v235, 0x1b000, v244
	v_add_u32_e32 v243, 1, v184
	v_cmp_ge_u32_e64 s[6:7], v243, v93
	v_cmp_lt_u32_e64 s[8:9], v243, v94
	v_sub_u32_e32 v244, v243, v92
	s_and_b64 s[98:99], s[6:7], s[8:9]
	v_max_i32_e32 v244, -15, v244
	v_add_u32_e32 v244, 15, v244
	v_min_u32_e32 v244, 30, v244
	v_cndmask_b32_e64 v244, 31, v244, s[98:99]
	v_lshl_add_u32 v244, v244, 2, 0
	v_add_u32_e32 v236, 0x1b000, v244
	v_add_u32_e32 v243, 2, v184
	v_cmp_ge_u32_e64 s[6:7], v243, v93
	v_cmp_lt_u32_e64 s[8:9], v243, v94
	v_sub_u32_e32 v244, v243, v92
	s_and_b64 s[98:99], s[6:7], s[8:9]
	v_max_i32_e32 v244, -15, v244
	v_add_u32_e32 v244, 15, v244
	v_min_u32_e32 v244, 30, v244
	v_cndmask_b32_e64 v244, 31, v244, s[98:99]
	v_lshl_add_u32 v244, v244, 2, 0
	v_add_u32_e32 v237, 0x1b000, v244
	v_add_u32_e32 v243, 3, v184
	v_cmp_ge_u32_e64 s[6:7], v243, v93
	v_cmp_lt_u32_e64 s[8:9], v243, v94
	v_sub_u32_e32 v244, v243, v92
	s_and_b64 s[98:99], s[6:7], s[8:9]
	v_max_i32_e32 v244, -15, v244
	v_add_u32_e32 v244, 15, v244
	v_min_u32_e32 v244, 30, v244
	v_cndmask_b32_e64 v244, 31, v244, s[98:99]
	v_lshl_add_u32 v244, v244, 2, 0
	v_add_u32_e32 v238, 0x1b000, v244
	v_add_u32_e32 v243, 4, v184
	v_cmp_ge_u32_e64 s[6:7], v243, v93
	v_cmp_lt_u32_e64 s[8:9], v243, v94
	v_sub_u32_e32 v244, v243, v92
	s_and_b64 s[98:99], s[6:7], s[8:9]
	v_max_i32_e32 v244, -15, v244
	v_add_u32_e32 v244, 15, v244
; __device__ __forceinline__ void na_item(const Params& p, int item, char* lds) {
;     ...
;   if (half == 0) {
;     const int qc = n * 16 + lr;
;     const int wstart = min(max(qc - 8, 0), 48);
; #pragma unroll
;     for (int ch = 0; ch < 8; ++ch)
; #pragma unroll
;       for (int ab = 0; ab < 2; ++ab)
; #pragma unroll
;         for (int e = 0; e < 4; ++e) {
;           const int kcol = band + 8 * lq + 4 * ab + e;
;           const bool inw = (kcol >= wstart) && (kcol < wstart + 16);
;           const int ci = min(max(kcol - qc + 15, 0), 30);
;           const float bv = rp[ch * 32 + ci];
;           s[ch * 2 + ab][e] = inw ? (s[ch * 2 + ab][e] + bv) : -INFINITY;
;         }
;   }
	v_min_u32_e32 v244, 30, v244
	v_cndmask_b32_e64 v244, 31, v244, s[98:99]
	v_lshl_add_u32 v244, v244, 2, 0
	v_add_u32_e32 v239, 0x1b000, v244
	v_add_u32_e32 v243, 5, v184
	v_cmp_ge_u32_e64 s[6:7], v243, v93
	v_cmp_lt_u32_e64 s[8:9], v243, v94
	v_sub_u32_e32 v244, v243, v92
	s_and_b64 s[98:99], s[6:7], s[8:9]
	v_max_i32_e32 v244, -15, v244
	v_add_u32_e32 v244, 15, v244
	v_min_u32_e32 v244, 30, v244
	v_cndmask_b32_e64 v244, 31, v244, s[98:99]
	v_lshl_add_u32 v244, v244, 2, 0
	v_add_u32_e32 v240, 0x1b000, v244
	v_add_u32_e32 v243, 6, v184
	v_cmp_ge_u32_e64 s[6:7], v243, v93
	v_cmp_lt_u32_e64 s[8:9], v243, v94
	v_sub_u32_e32 v244, v243, v92
	s_and_b64 s[98:99], s[6:7], s[8:9]
	v_max_i32_e32 v244, -15, v244
	v_add_u32_e32 v244, 15, v244
	v_min_u32_e32 v244, 30, v244
	v_cndmask_b32_e64 v244, 31, v244, s[98:99]
	v_lshl_add_u32 v244, v244, 2, 0
	v_add_u32_e32 v241, 0x1b000, v244
	v_add_u32_e32 v243, 7, v184
	v_cmp_ge_u32_e64 s[6:7], v243, v93
	v_cmp_lt_u32_e64 s[8:9], v243, v94
	v_sub_u32_e32 v244, v243, v92
	s_and_b64 s[98:99], s[6:7], s[8:9]
	v_max_i32_e32 v244, -15, v244
	v_add_u32_e32 v244, 15, v244
	v_min_u32_e32 v244, 30, v244
	v_cndmask_b32_e64 v244, 31, v244, s[98:99]
	v_lshl_add_u32 v244, v244, 2, 0
	v_add_u32_e32 v242, 0x1b000, v244
	v_cmp_ge_u32_e64 s[6:7], v184, v93
	v_cmp_lt_u32_e64 s[8:9], v184, v94
	v_sub_u32_e32 v72, v184, v92
	s_and_b64 s[40:41], s[6:7], s[8:9]
	v_mov_b32_e32 v73, 0xff800000
	v_max_i32_e32 v185, -15, v72
	v_mov_b32_e32 v72, 0xff800000
	ds_read_b32 v245, v235
	ds_read_b32 v246, v236
	ds_read_b32 v247, v237
	ds_read_b32 v248, v238
	ds_read_b32 v249, v239
	ds_read_b32 v250, v240
	ds_read_b32 v251, v241
	ds_read_b32 v252, v242
	ds_read_b32 v253, v235 offset:128
	ds_read_b32 v254, v236 offset:128
	ds_read_b32 v255, v237 offset:128
	ds_read_b32 v243, v238 offset:128
	s_waitcnt lgkmcnt(6)
	v_add_f32_e32 v72, v140, v245
	v_or_b32_e32 v74, 1, v184
	v_cmp_ge_u32_e64 s[6:7], v74, v93
	v_cmp_lt_u32_e64 s[8:9], v74, v94
	v_sub_u32_e32 v74, v74, v92
	s_and_b64 s[42:43], s[6:7], s[8:9]
	v_max_i32_e32 v140, -15, v74
	v_add_f32_e32 v73, v141, v246
	v_or_b32_e32 v74, 2, v184
	v_cmp_ge_u32_e64 s[6:7], v74, v93
	v_cmp_lt_u32_e64 s[8:9], v74, v94
	v_sub_u32_e32 v74, v74, v92
	s_and_b64 s[44:45], s[6:7], s[8:9]
	v_mov_b32_e32 v75, 0xff800000
	v_max_i32_e32 v141, -15, v74
	v_mov_b32_e32 v74, 0xff800000
	v_add_f32_e32 v74, v142, v247
	v_or_b32_e32 v84, 3, v184
	v_cmp_ge_u32_e64 s[6:7], v84, v93
	v_cmp_lt_u32_e64 s[8:9], v84, v94
	v_sub_u32_e32 v84, v84, v92
	s_and_b64 s[46:47], s[6:7], s[8:9]
	v_max_i32_e32 v142, -15, v84
	v_add_f32_e32 v75, v143, v248
	v_or_b32_e32 v84, 4, v184
	v_cmp_ge_u32_e64 s[6:7], v84, v93
	v_cmp_lt_u32_e64 s[8:9], v84, v94
	v_sub_u32_e32 v84, v84, v92
	s_and_b64 s[52:53], s[6:7], s[8:9]
	v_mov_b32_e32 v85, 0xff800000
	v_max_i32_e32 v143, -15, v84
	v_mov_b32_e32 v84, 0xff800000
	v_add_f32_e32 v84, v136, v249
	v_or_b32_e32 v86, 5, v184
	v_cmp_ge_u32_e64 s[6:7], v86, v93
	v_cmp_lt_u32_e64 s[8:9], v86, v94
	v_sub_u32_e32 v86, v86, v92
	s_and_b64 s[54:55], s[6:7], s[8:9]
	v_max_i32_e32 v136, -15, v86
	v_add_f32_e32 v85, v137, v250
	v_or_b32_e32 v86, 6, v184
	v_cmp_ge_u32_e64 s[6:7], v86, v93
	v_cmp_lt_u32_e64 s[8:9], v86, v94
	v_sub_u32_e32 v86, v86, v92
	s_and_b64 s[56:57], s[6:7], s[8:9]
	v_mov_b32_e32 v87, 0xff800000
	v_max_i32_e32 v137, -15, v86
	v_mov_b32_e32 v86, 0xff800000
	ds_read_b32 v245, v239 offset:128
	ds_read_b32 v246, v240 offset:128
	ds_read_b32 v247, v241 offset:128
	ds_read_b32 v248, v242 offset:128
	ds_read_b32 v249, v235 offset:256
	ds_read_b32 v250, v236 offset:256
	s_waitcnt lgkmcnt(6)
	v_add_f32_e32 v86, v138, v251
	v_or_b32_e32 v95, 7, v184
	v_cmp_ge_u32_e64 s[6:7], v95, v93
	v_cmp_lt_u32_e64 s[8:9], v95, v94
	v_sub_u32_e32 v92, v95, v92
	s_and_b64 s[6:7], s[6:7], s[8:9]
	v_max_i32_e32 v138, -15, v92
	v_add_f32_e32 v87, v139, v252
	v_mov_b32_e32 v93, 0xff800000
	v_mov_b32_e32 v92, 0xff800000
	v_add_f32_e32 v92, v132, v253
	v_add_f32_e32 v93, v133, v254
	v_mov_b32_e32 v95, 0xff800000
	v_mov_b32_e32 v94, 0xff800000
	v_add_f32_e32 v94, v134, v255
	v_add_f32_e32 v95, v135, v243
	v_mov_b32_e32 v97, 0xff800000
	v_mov_b32_e32 v96, 0xff800000
	ds_read_b32 v251, v237 offset:256
	ds_read_b32 v252, v238 offset:256
	ds_read_b32 v253, v239 offset:256
	ds_read_b32 v254, v240 offset:256
	ds_read_b32 v255, v241 offset:256
	ds_read_b32 v243, v242 offset:256
	s_waitcnt lgkmcnt(6)
	v_add_f32_e32 v96, v124, v245
	v_add_f32_e32 v97, v125, v246
	v_mov_b32_e32 v99, 0xff800000
	v_mov_b32_e32 v98, 0xff800000
	v_add_f32_e32 v98, v126, v247
	v_add_f32_e32 v99, v127, v248
	v_mov_b32_e32 v105, 0xff800000
	v_mov_b32_e32 v104, 0xff800000
	v_add_f32_e32 v104, v116, v249
	v_add_f32_e32 v105, v117, v250
	v_mov_b32_e32 v107, 0xff800000
	v_mov_b32_e32 v106, 0xff800000
	ds_read_b32 v245, v235 offset:384
	ds_read_b32 v246, v236 offset:384
	ds_read_b32 v247, v237 offset:384
	ds_read_b32 v248, v238 offset:384
	ds_read_b32 v249, v239 offset:384
	ds_read_b32 v250, v240 offset:384
	s_waitcnt lgkmcnt(6)
; __device__ __forceinline__ void na_item(const Params& p, int item, char* lds) {
;     ...
;   if (half == 0) {
;     const int qc = n * 16 + lr;
;     const int wstart = min(max(qc - 8, 0), 48);
; #pragma unroll
;     for (int ch = 0; ch < 8; ++ch)
; #pragma unroll
;       for (int ab = 0; ab < 2; ++ab)
; #pragma unroll
;         for (int e = 0; e < 4; ++e) {
;           const int kcol = band + 8 * lq + 4 * ab + e;
;           const bool inw = (kcol >= wstart) && (kcol < wstart + 16);
;           const int ci = min(max(kcol - qc + 15, 0), 30);
;           const float bv = rp[ch * 32 + ci];
;           s[ch * 2 + ab][e] = inw ? (s[ch * 2 + ab][e] + bv) : -INFINITY;
;         }
;   }
	v_add_f32_e32 v106, v118, v251
	v_add_f32_e32 v107, v119, v252
	v_mov_b32_e32 v113, 0xff800000
	v_mov_b32_e32 v112, 0xff800000
	v_add_f32_e32 v112, v108, v253
	v_add_f32_e32 v113, v109, v254
	v_mov_b32_e32 v115, 0xff800000
	v_mov_b32_e32 v114, 0xff800000
	v_add_f32_e32 v114, v110, v255
	v_add_f32_e32 v115, v111, v243
	v_mov_b32_e32 v121, 0xff800000
	v_mov_b32_e32 v120, 0xff800000
	ds_read_b32 v251, v241 offset:384
	ds_read_b32 v252, v242 offset:384
	ds_read_b32 v253, v235 offset:512
	ds_read_b32 v254, v236 offset:512
	ds_read_b32 v255, v237 offset:512
	ds_read_b32 v243, v238 offset:512
	s_waitcnt lgkmcnt(6)
	v_add_f32_e32 v120, v100, v245
	v_add_f32_e32 v121, v101, v246
	v_mov_b32_e32 v123, 0xff800000
	v_mov_b32_e32 v122, 0xff800000
	v_add_f32_e32 v122, v102, v247
	v_add_f32_e32 v123, v103, v248
	v_mov_b32_e32 v129, 0xff800000
	v_mov_b32_e32 v128, 0xff800000
	v_add_f32_e32 v128, v88, v249
	v_add_f32_e32 v129, v89, v250
	v_mov_b32_e32 v131, 0xff800000
	v_mov_b32_e32 v130, 0xff800000
	ds_read_b32 v245, v239 offset:512
	ds_read_b32 v246, v240 offset:512
	ds_read_b32 v247, v241 offset:512
	ds_read_b32 v248, v242 offset:512
	ds_read_b32 v249, v235 offset:640
	ds_read_b32 v250, v236 offset:640
	s_waitcnt lgkmcnt(6)
	v_add_f32_e32 v130, v90, v251
	v_add_f32_e32 v131, v91, v252
	v_mov_b32_e32 v89, 0xff800000
	v_mov_b32_e32 v88, 0xff800000
	v_add_f32_e32 v88, v80, v253
	v_add_f32_e32 v89, v81, v254
	v_mov_b32_e32 v91, 0xff800000
	v_mov_b32_e32 v90, 0xff800000
	v_add_f32_e32 v90, v82, v255
	v_add_f32_e32 v91, v83, v243
	v_mov_b32_e32 v81, 0xff800000
	v_mov_b32_e32 v80, 0xff800000
	ds_read_b32 v251, v237 offset:640
	ds_read_b32 v252, v238 offset:640
	ds_read_b32 v253, v239 offset:640
	ds_read_b32 v254, v240 offset:640
	ds_read_b32 v255, v241 offset:640
	ds_read_b32 v243, v242 offset:640
	s_waitcnt lgkmcnt(6)
	v_add_f32_e32 v80, v76, v245
	v_add_f32_e32 v81, v77, v246
	v_mov_b32_e32 v83, 0xff800000
	v_mov_b32_e32 v82, 0xff800000
	v_add_f32_e32 v82, v78, v247
	v_add_f32_e32 v83, v79, v248
	v_mov_b32_e32 v77, 0xff800000
	v_mov_b32_e32 v76, 0xff800000
	v_add_f32_e32 v76, v68, v249
	v_add_f32_e32 v77, v69, v250
	v_mov_b32_e32 v79, 0xff800000
	v_mov_b32_e32 v78, 0xff800000
	ds_read_b32 v245, v235 offset:768
	ds_read_b32 v246, v236 offset:768
	ds_read_b32 v247, v237 offset:768
	ds_read_b32 v248, v238 offset:768
	ds_read_b32 v249, v239 offset:768
	ds_read_b32 v250, v240 offset:768
	s_waitcnt lgkmcnt(6)
	v_add_f32_e32 v78, v70, v251
	v_add_f32_e32 v79, v71, v252
	v_mov_b32_e32 v69, 0xff800000
	v_mov_b32_e32 v68, 0xff800000
	v_add_f32_e32 v68, v64, v253
	v_add_f32_e32 v69, v65, v254
	v_mov_b32_e32 v71, 0xff800000
	v_mov_b32_e32 v70, 0xff800000
	v_add_f32_e32 v70, v66, v255
	v_add_f32_e32 v71, v67, v243
	v_mov_b32_e32 v65, 0xff800000
	v_mov_b32_e32 v64, 0xff800000
	ds_read_b32 v251, v241 offset:768
	ds_read_b32 v252, v242 offset:768
	ds_read_b32 v253, v235 offset:896
	ds_read_b32 v254, v236 offset:896
	ds_read_b32 v255, v237 offset:896
	ds_read_b32 v243, v238 offset:896
	s_waitcnt lgkmcnt(6)
	v_add_f32_e32 v64, v60, v245
	v_add_f32_e32 v65, v61, v246
	v_mov_b32_e32 v67, 0xff800000
	v_mov_b32_e32 v66, 0xff800000
	v_add_f32_e32 v66, v62, v247
	v_add_f32_e32 v67, v63, v248
	v_mov_b32_e32 v61, 0xff800000
	v_mov_b32_e32 v60, 0xff800000
	v_add_f32_e32 v60, v56, v249
	v_add_f32_e32 v61, v57, v250
	v_mov_b32_e32 v63, 0xff800000
	v_mov_b32_e32 v62, 0xff800000
	ds_read_b32 v245, v239 offset:896
	ds_read_b32 v246, v240 offset:896
	ds_read_b32 v247, v241 offset:896
	ds_read_b32 v248, v242 offset:896
	s_waitcnt lgkmcnt(4)
	v_add_f32_e32 v62, v58, v251
	v_add_f32_e32 v63, v59, v252
	v_mov_b32_e32 v57, 0xff800000
	v_mov_b32_e32 v56, 0xff800000
	v_add_f32_e32 v56, v52, v253
	v_add_f32_e32 v57, v53, v254
	v_mov_b32_e32 v59, 0xff800000
	v_mov_b32_e32 v58, 0xff800000
	v_add_f32_e32 v58, v54, v255
	v_add_f32_e32 v59, v55, v243
	v_mov_b32_e32 v53, 0xff800000
	v_mov_b32_e32 v52, 0xff800000
	s_waitcnt lgkmcnt(0)
	v_add_f32_e32 v52, v0, v245
	v_add_f32_e32 v53, v1, v246
	v_mov_b32_e32 v55, 0xff800000
	v_mov_b32_e32 v54, 0xff800000
	v_add_f32_e32 v54, v2, v247
	v_add_f32_e32 v55, v3, v248
	v_mov_b64_e32 v[0:1], v[52:53]
	v_mov_b64_e32 v[2:3], v[54:55]
	v_mov_b64_e32 v[52:53], v[56:57]
	v_mov_b64_e32 v[54:55], v[58:59]
	v_mov_b64_e32 v[56:57], v[60:61]
	v_mov_b64_e32 v[58:59], v[62:63]
	v_mov_b64_e32 v[60:61], v[64:65]
	v_mov_b64_e32 v[62:63], v[66:67]
	v_mov_b64_e32 v[64:65], v[68:69]
	v_mov_b64_e32 v[66:67], v[70:71]
	v_mov_b64_e32 v[68:69], v[76:77]
	v_mov_b64_e32 v[70:71], v[78:79]
	v_mov_b64_e32 v[76:77], v[80:81]
	v_mov_b64_e32 v[78:79], v[82:83]
	v_mov_b64_e32 v[80:81], v[88:89]
	v_mov_b64_e32 v[82:83], v[90:91]
	v_mov_b64_e32 v[142:143], v[74:75]
	v_mov_b64_e32 v[138:139], v[86:87]
	v_mov_b64_e32 v[134:135], v[94:95]
	v_mov_b64_e32 v[126:127], v[98:99]
	v_mov_b64_e32 v[118:119], v[106:107]
	v_mov_b64_e32 v[108:109], v[112:113]
	v_mov_b64_e32 v[100:101], v[120:121]
	v_mov_b64_e32 v[88:89], v[128:129]
	v_mov_b32_e32 v185, 0x410
	v_mov_b64_e32 v[140:141], v[72:73]
	v_mov_b64_e32 v[136:137], v[84:85]
	v_mov_b64_e32 v[132:133], v[92:93]
	v_mov_b64_e32 v[124:125], v[96:97]
	v_mov_b64_e32 v[116:117], v[104:105]
	v_mov_b64_e32 v[110:111], v[114:115]
	v_mov_b64_e32 v[102:103], v[122:123]
	v_mov_b64_e32 v[90:91], v[130:131]
